# attention PV block: key-half-major MFMA order, second half of the softmax (8 exp, packs) in the shadow of the first eight PV MFMAs
# speedup vs baseline: 1.0047x; 1.0047x over previous
.LBB0_308:
	v_sub_f32_e32 v0, v160, v215
	v_exp_f32_e32 v0, v0
	v_sub_f32_e32 v160, v161, v215
	v_exp_f32_e32 v160, v160
	v_sub_f32_e32 v161, v162, v215
	v_exp_f32_e32 v161, v161
	v_sub_f32_e32 v162, v163, v215
	v_exp_f32_e32 v162, v162
	v_sub_f32_e32 v164, v164, v215
	v_add_f32_e32 v163, v207, v0
	v_exp_f32_e32 v164, v164
	v_add_f32_e32 v163, v160, v163
	v_add_f32_e32 v163, v161, v163
	v_sub_f32_e32 v165, v165, v215
	v_add_f32_e32 v163, v162, v163
	v_exp_f32_e32 v165, v165
	v_sub_f32_e32 v166, v166, v215
	v_exp_f32_e32 v166, v166
	v_sub_f32_e32 v167, v167, v215
	v_add_f32_e32 v163, v164, v163
	v_exp_f32_e32 v167, v167
	v_cvt_pk_bf16_f32 v160, v0, v160
	v_cvt_pk_bf16_f32 v161, v161, v162
	v_add_f32_e32 v163, v165, v163
	v_cvt_pk_bf16_f32 v162, v164, v165
	v_add_f32_e32 v163, v166, v163
	v_add_f32_e32 v175, v167, v163
	v_cvt_pk_bf16_f32 v163, v166, v167
	s_nop 0
	s_waitcnt lgkmcnt(3)
	v_mfma_f32_32x32x16_bf16 v[128:143], v[148:151], v[160:163], v[128:143]
	ds_read_b128 v[148:151], v174 offset:27648
	v_sub_f32_e32 v164, v169, v215
	v_sub_f32_e32 v0, v168, v215
	v_exp_f32_e32 v168, v164
	s_waitcnt lgkmcnt(3)
	v_mfma_f32_32x32x16_bf16 v[112:127], v[144:147], v[160:163], v[112:127]
	ds_read_b128 v[144:147], v174 offset:30208
	v_sub_f32_e32 v164, v170, v215
	v_exp_f32_e32 v169, v164
	v_sub_f32_e32 v165, v171, v215
	s_waitcnt lgkmcnt(3)
	v_mfma_f32_32x32x16_bf16 v[96:111], v[156:159], v[160:163], v[96:111]
	ds_read_b128 v[156:159], v174 offset:32768
	v_exp_f32_e32 v170, v165
	v_sub_f32_e32 v164, v172, v215
	v_exp_f32_e32 v171, v164
	s_waitcnt lgkmcnt(3)
	v_mfma_f32_32x32x16_bf16 v[80:95], v[152:155], v[160:163], v[80:95]
	ds_read_b128 v[152:155], v174 offset:35328
	v_sub_f32_e32 v164, v173, v215
	v_sub_f32_e32 v14, v14, v215
	v_sub_f32_e32 v15, v15, v215
	s_waitcnt lgkmcnt(3)
	v_mfma_f32_32x32x16_bf16 v[64:79], v[148:151], v[160:163], v[64:79]
	ds_read_b128 v[148:151], v174 offset:17440
	v_exp_f32_e32 v0, v0
	v_exp_f32_e32 v172, v164
	s_waitcnt lgkmcnt(3)
	v_mfma_f32_32x32x16_bf16 v[48:63], v[144:147], v[160:163], v[48:63]
	ds_read_b128 v[144:147], v174 offset:20000
	v_exp_f32_e32 v14, v14
	v_exp_f32_e32 v15, v15
	s_waitcnt lgkmcnt(3)
	v_mfma_f32_32x32x16_bf16 v[32:47], v[156:159], v[160:163], v[32:47]
	ds_read_b128 v[156:159], v174 offset:22560
	v_cvt_pk_bf16_f32 v164, v0, v168
	v_cvt_pk_bf16_f32 v165, v169, v170
	s_waitcnt lgkmcnt(3)
	v_mfma_f32_32x32x16_bf16 v[16:31], v[152:155], v[160:163], v[16:31]
	ds_read_b128 v[152:155], v174 offset:25120
	v_cvt_pk_bf16_f32 v166, v171, v172
	v_cvt_pk_bf16_f32 v167, v14, v15
	s_nop 1
	s_waitcnt lgkmcnt(3)
	v_mfma_f32_32x32x16_bf16 v[128:143], v[148:151], v[164:167], v[128:143]
	ds_read_b128 v[148:151], v174 offset:27680
	s_waitcnt lgkmcnt(3)
	v_mfma_f32_32x32x16_bf16 v[112:127], v[144:147], v[164:167], v[112:127]
	ds_read_b128 v[144:147], v174 offset:30240
	v_subrev_u32_e32 v250, s73, v213
	s_waitcnt vmcnt(2)
	ds_write_b128 v250, v[2:5] offset:37888
	ds_write_b128 v250, v[6:9] offset:46592
	s_waitcnt lgkmcnt(5)
	v_mfma_f32_32x32x16_bf16 v[96:111], v[156:159], v[164:167], v[96:111]
	ds_read_b128 v[156:159], v174 offset:32800
	s_waitcnt lgkmcnt(5)
	v_mfma_f32_32x32x16_bf16 v[80:95], v[152:155], v[164:167], v[80:95]
	ds_read_b128 v[152:155], v174 offset:35360
	s_waitcnt lgkmcnt(5)
	v_mfma_f32_32x32x16_bf16 v[64:79], v[148:151], v[164:167], v[64:79]
	s_waitcnt lgkmcnt(4)
	v_mfma_f32_32x32x16_bf16 v[48:63], v[144:147], v[164:167], v[48:63]
	v_subrev_u32_e32 v250, s73, v214
	v_add_u32_e32 v2, 0xd800, v250
	v_add_u32_e32 v250, 0x10000, v250
	s_waitcnt vmcnt(0)
	ds_write2_b64 v2, v[10:11], v[12:13] offset1:2
	ds_write2_b64 v250, v[176:177], v[178:179] offset1:2
	s_waitcnt lgkmcnt(3)
	v_mfma_f32_32x32x16_bf16 v[32:47], v[156:159], v[164:167], v[32:47]
	s_waitcnt lgkmcnt(2)
	v_mfma_f32_32x32x16_bf16 v[16:31], v[152:155], v[164:167], v[16:31]
	v_add_f32_e32 v0, v0, v175
	v_add_f32_e32 v0, v168, v0
	v_add_f32_e32 v0, v169, v0
	v_add_f32_e32 v0, v170, v0
	v_add_f32_e32 v0, v171, v0
	v_add_f32_e32 v0, v172, v0
	v_add_f32_e32 v0, v14, v0
	v_add_f32_e32 v207, v15, v0
	s_add_i32 s77, s77, 1
	v_lshl_add_u64 v[188:189], v[188:189], 0, 64
	s_mov_b64 vcc, 0x80000
	s_cmp_eq_u32 s79, s77
	v_lshl_add_u64 v[190:191], v[190:191], 0, vcc
	s_branch .Lat_step_end

.Lat_nostag:
	v_lshl_add_u64 v[2:3], s[30:31], 0, v[190:191]
	s_mov_b32 s73, 0x13481000
	v_add_co_u32_e32 v6, vcc, s73, v2
	v_lshl_add_u64 v[10:11], s[30:31], 0, v[188:189]
	s_nop 0
	v_addc_co_u32_e32 v7, vcc, 0, v3, vcc
	v_add_co_u32_e32 v12, vcc, 0x1f400000, v10
	global_load_dwordx4 v[2:5], v[6:7], off
	s_nop 0
	global_load_dwordx4 v[6:9], v[6:7], off offset:256
	v_addc_co_u32_e32 v13, vcc, 0, v11, vcc
	v_add_co_u32_e32 v14, vcc, 0x1f480000, v10
	s_bitcmp1_b32 s77, 0
	s_nop 0
	v_addc_co_u32_e32 v15, vcc, 0, v11, vcc
	global_load_dwordx4 v[10:13], v[12:13], off offset:64
	s_nop 0
	global_load_dwordx4 v[176:179], v[14:15], off offset:64
	s_cselect_b32 s73, 0x9400, 0
	s_cmp_gt_u32 s77, s49
	s_cbranch_scc1 .LBB0_309
	s_add_i32 vcc_lo, s73, 0
	s_add_i32 vcc_hi, vcc_lo, s78
	v_add3_u32 v0, vcc_hi, v211, v209
	v_add_u32_e32 v14, v210, v209
	ds_read_b128 v[144:147], v0
	ds_read_b128 v[160:163], v0 offset:32
	ds_read_b128 v[148:151], v14
	ds_read_b128 v[164:167], v14 offset:32
	ds_read_b128 v[216:219], v0 offset:64
	ds_read_b128 v[220:223], v0 offset:96
	ds_read_b128 v[224:227], v14 offset:64
	ds_read_b128 v[228:231], v14 offset:96
	v_add_u32_e32 v250, vcc_lo, v212
	s_waitcnt lgkmcnt(5)
	v_mfma_f32_32x32x16_bf16 v[144:159], v[144:147], v[148:151], 0
	s_waitcnt lgkmcnt(4)
	v_mfma_f32_32x32x16_bf16 v[160:175], v[160:163], v[164:167], 0
	s_waitcnt lgkmcnt(1)
	v_mfma_f32_32x32x16_bf16 v[144:159], v[216:219], v[224:227], v[144:159]
	ds_read_b128 v[216:219], v0 offset:128
	ds_read_b128 v[224:227], v0 offset:160
	ds_read_b128 v[232:235], v14 offset:128
	ds_read_b128 v[236:239], v14 offset:160
	ds_read_b128 v[240:243], v0 offset:192
	ds_read_b128 v[244:247], v0 offset:224
	ds_read_b128 v[180:183], v14 offset:192
	ds_read_b128 v[184:187], v14 offset:224
	s_waitcnt lgkmcnt(8)
	v_mfma_f32_32x32x16_bf16 v[160:175], v[220:223], v[228:231], v[160:175]
	s_waitcnt lgkmcnt(5)
	v_mfma_f32_32x32x16_bf16 v[144:159], v[216:219], v[232:235], v[144:159]
	s_waitcnt lgkmcnt(4)
	v_mfma_f32_32x32x16_bf16 v[160:175], v[224:227], v[236:239], v[160:175]
	s_waitcnt lgkmcnt(1)
	v_mfma_f32_32x32x16_bf16 v[144:159], v[240:243], v[180:183], v[144:159]
	s_waitcnt lgkmcnt(0)
	v_mfma_f32_32x32x16_bf16 v[160:175], v[244:247], v[184:187], v[160:175]
	s_nop 11
	v_pk_add_f32 v[14:15], v[158:159], v[174:175]
	v_add_u32_e32 v174, v250, v208
	v_pk_add_f32 v[166:167], v[150:151], v[166:167]
	v_pk_add_f32 v[164:165], v[148:149], v[164:165]
	v_pk_add_f32 v[162:163], v[146:147], v[162:163]
	v_pk_add_f32 v[160:161], v[144:145], v[160:161]
	ds_read_b128 v[148:151], v174 offset:17408
	ds_read_b128 v[144:147], v174 offset:19968
	v_pk_add_f32 v[172:173], v[156:157], v[172:173]
	v_pk_add_f32 v[170:171], v[154:155], v[170:171]
	v_pk_add_f32 v[168:169], v[152:153], v[168:169]
	ds_read_b128 v[156:159], v174 offset:22528
	ds_read_b128 v[152:155], v174 offset:25088
	s_cmp_lg_u32 s49, s77
	s_cbranch_scc1 .LBB0_313
	v_cndmask_b32_e64 v0, v160, v202, s[90:91]
	v_cndmask_b32_e64 v161, v202, v161, s[88:89]
	v_cndmask_b32_e64 v160, v0, v160, s[88:89]
	v_cndmask_b32_e64 v162, v162, v202, s[92:93]
	v_cndmask_b32_e64 v163, v163, v202, s[94:95]
	v_cndmask_b32_e64 v164, v164, v202, s[96:97]
	v_cndmask_b32_e64 v165, v165, v202, s[4:5]
	v_cndmask_b32_e64 v166, v166, v202, s[6:7]
	v_cndmask_b32_e64 v167, v167, v202, s[8:9]
	v_cndmask_b32_e64 v168, v168, v202, s[10:11]
	v_cndmask_b32_e64 v169, v169, v202, s[12:13]
	v_cndmask_b32_e64 v170, v170, v202, s[14:15]
	v_cndmask_b32_e64 v171, v171, v202, s[16:17]
	v_cndmask_b32_e64 v172, v172, v202, s[18:19]
	v_cndmask_b32_e64 v173, v173, v202, s[20:21]
	v_cndmask_b32_e64 v14, v14, v202, s[22:23]
	v_cndmask_b32_e64 v15, v15, v202, s[24:25]
